# Win/Wup (ids 4,5) conversion item loops in the idle tail of phase 1 de-serialised: 8 slab loads + gains issued together, one wait
# speedup vs baseline: 1.0014x; 1.0014x over previous
.Lcv_t4_tr:
	s_waitcnt lgkmcnt(0)
	ds_read2_b32 v[2:3], v1 offset1:36
	v_or_b32_e32 v6, s12, v8
	s_waitcnt lgkmcnt(0)
	v_cvt_pk_bf16_f32 v2, v2, v3
	ds_read2_b32 v[4:5], v1 offset0:72 offset1:108
	s_ashr_i32 s9, s8, 31
	v_ashrrev_i32_e32 v7, 31, v6
	s_waitcnt lgkmcnt(0)
	v_cvt_pk_bf16_f32 v3, v4, v5
	ds_read2_b32 v[4:5], v1 offset0:144 offset1:180
	v_lshl_add_u64 v[20:21], s[8:9], 1, v[16:17]
	v_lshlrev_b64 v[6:7], 11, v[6:7]
	s_waitcnt lgkmcnt(0)
	v_cvt_pk_bf16_f32 v4, v4, v5
	ds_read2_b32 v[18:19], v1 offset0:216 offset1:252
	v_lshl_add_u64 v[6:7], v[20:21], 0, v[6:7]
	s_waitcnt lgkmcnt(0)
	v_cvt_pk_bf16_f32 v5, v18, v19
	v_or_b32_e32 v18, s12, v25
	global_store_dwordx4 v[6:7], v[2:5], off sc1
	s_nop 1
	ds_read2_b32 v[2:3], v1 offset0:8 offset1:44
	s_waitcnt lgkmcnt(0)
	v_cvt_pk_bf16_f32 v2, v2, v3
	ds_read2_b32 v[4:5], v1 offset0:80 offset1:116
	v_ashrrev_i32_e32 v19, 31, v18
	s_waitcnt lgkmcnt(0)
	v_cvt_pk_bf16_f32 v3, v4, v5
	ds_read2_b32 v[4:5], v1 offset0:152 offset1:188
	v_add_u32_e32 v10, 0x200, v1
	v_lshlrev_b64 v[18:19], 11, v[18:19]
	s_waitcnt lgkmcnt(0)
	v_cvt_pk_bf16_f32 v4, v4, v5
	ds_read2_b32 v[6:7], v10 offset0:96 offset1:132
	v_lshl_add_u64 v[18:19], v[20:21], 0, v[18:19]
	s_waitcnt lgkmcnt(0)
	v_cvt_pk_bf16_f32 v5, v6, v7
	s_add_i32 s4, s2, 0x400
	global_store_dwordx4 v[18:19], v[2:5], off sc1
	s_nop 1
	ds_read2_b32 v[2:3], v1 offset0:16 offset1:52
	v_or_b32_e32 v18, s12, v26
	s_waitcnt lgkmcnt(0)
	v_cvt_pk_bf16_f32 v2, v2, v3
	ds_read2_b32 v[4:5], v1 offset0:88 offset1:124
	v_ashrrev_i32_e32 v19, 31, v18
	s_waitcnt lgkmcnt(0)
	v_cvt_pk_bf16_f32 v3, v4, v5
	ds_read2_b32 v[4:5], v1 offset0:160 offset1:196
	v_lshlrev_b64 v[18:19], 11, v[18:19]
	s_waitcnt lgkmcnt(0)
	v_cvt_pk_bf16_f32 v4, v4, v5
	ds_read2_b32 v[6:7], v10 offset0:104 offset1:140
	v_lshl_add_u64 v[18:19], v[20:21], 0, v[18:19]
	s_waitcnt lgkmcnt(0)
	v_cvt_pk_bf16_f32 v5, v6, v7
	s_cmp_gt_u32 s2, 0xfffffbff
	global_store_dwordx4 v[18:19], v[2:5], off sc1
	s_nop 1
	ds_read2_b32 v[2:3], v1 offset0:24 offset1:60
	s_waitcnt lgkmcnt(0)
	v_cvt_pk_bf16_f32 v2, v2, v3
	ds_read2_b32 v[4:5], v1 offset0:96 offset1:132
	v_or_b32_e32 v18, s12, v27
	s_waitcnt lgkmcnt(0)
	v_cvt_pk_bf16_f32 v3, v4, v5
	ds_read2_b32 v[4:5], v1 offset0:168 offset1:204
	v_ashrrev_i32_e32 v19, 31, v18
	s_waitcnt lgkmcnt(0)
	v_cvt_pk_bf16_f32 v4, v4, v5
	ds_read2_b32 v[6:7], v10 offset0:112 offset1:148
	v_lshlrev_b64 v[18:19], 11, v[18:19]
	s_waitcnt lgkmcnt(0)
	v_cvt_pk_bf16_f32 v5, v6, v7
	v_lshl_add_u64 v[6:7], v[20:21], 0, v[18:19]
	global_store_dwordx4 v[6:7], v[2:5], off sc1
	s_nop 1
	s_waitcnt lgkmcnt(0)
	s_mov_b32 s2, s4
	s_cbranch_scc0 .LBB0_463

.LBB0_432:
	s_or_b64 exec, exec, s[4:5]
	s_sext_i32_i16 s4, s6
	s_lshr_b32 s4, s4, 6
	s_sext_i32_i16 s4, s4
	s_lshl_b32 s8, s4, 6
	v_cmp_ne_u64_e64 s[4:5], 0, v[20:21]
	v_cmp_ne_u64_e32 vcc, 0, v[18:19]
	s_ashr_i32 s9, s8, 31
	v_or_b32_e32 v80, s8, v8
	v_cmp_lt_i32_e64 s[6:7], v80, v33
	s_and_b64 s[10:11], s[4:5], s[6:7]
	v_mov_b32_e32 v96, 0
	v_mov_b32_e32 v97, 0
	v_mov_b32_e32 v98, 0
	v_mov_b32_e32 v99, 0
	v_mov_b32_e32 v160, 1.0
	s_and_saveexec_b64 s[6:7], s[10:11]
	v_mul_hi_i32_i24_e32 v129, v22, v80
	v_mul_i32_i24_e32 v128, v22, v80
	v_lshl_add_u64 v[128:129], v[128:129], 2, v[20:21]
	global_load_dwordx4 v[96:99], v[128:129], off nt
	s_and_saveexec_b64 s[10:11], vcc
	v_lshl_add_u64 v[144:145], s[8:9], 0, v[8:9]
	v_lshl_add_u64 v[144:145], v[144:145], 2, v[18:19]
	global_load_dword v160, v[144:145], off
	s_or_b64 exec, exec, s[10:11]
	s_or_b64 exec, exec, s[6:7]
	v_or_b32_e32 v82, s8, v25
	v_cmp_lt_i32_e64 s[6:7], v82, v33
	s_and_b64 s[10:11], s[4:5], s[6:7]
	v_mov_b32_e32 v100, 0
	v_mov_b32_e32 v101, 0
	v_mov_b32_e32 v102, 0
	v_mov_b32_e32 v103, 0
	v_mov_b32_e32 v161, 1.0
	s_and_saveexec_b64 s[6:7], s[10:11]
	v_mul_hi_i32_i24_e32 v131, v22, v82
	v_mul_i32_i24_e32 v130, v22, v82
	v_lshl_add_u64 v[130:131], v[130:131], 2, v[20:21]
	global_load_dwordx4 v[100:103], v[130:131], off nt
	s_and_saveexec_b64 s[10:11], vcc
	v_lshl_add_u64 v[146:147], s[8:9], 0, v[8:9]
	v_lshl_add_u64 v[146:147], v[146:147], 2, v[18:19]
	global_load_dword v161, v[146:147], off offset:32
	s_or_b64 exec, exec, s[10:11]
	s_or_b64 exec, exec, s[6:7]
	v_or_b32_e32 v84, s8, v26
	v_cmp_lt_i32_e64 s[6:7], v84, v33
	s_and_b64 s[10:11], s[4:5], s[6:7]
	v_mov_b32_e32 v104, 0
	v_mov_b32_e32 v105, 0
	v_mov_b32_e32 v106, 0
	v_mov_b32_e32 v107, 0
	v_mov_b32_e32 v162, 1.0
	s_and_saveexec_b64 s[6:7], s[10:11]
	v_mul_hi_i32_i24_e32 v133, v22, v84
	v_mul_i32_i24_e32 v132, v22, v84
	v_lshl_add_u64 v[132:133], v[132:133], 2, v[20:21]
	global_load_dwordx4 v[104:107], v[132:133], off nt
	s_and_saveexec_b64 s[10:11], vcc
	v_lshl_add_u64 v[148:149], s[8:9], 0, v[8:9]
	v_lshl_add_u64 v[148:149], v[148:149], 2, v[18:19]
	global_load_dword v162, v[148:149], off offset:64
	s_or_b64 exec, exec, s[10:11]
	s_or_b64 exec, exec, s[6:7]
	v_or_b32_e32 v86, s8, v27
	v_cmp_lt_i32_e64 s[6:7], v86, v33
	s_and_b64 s[10:11], s[4:5], s[6:7]
	v_mov_b32_e32 v108, 0
	v_mov_b32_e32 v109, 0
	v_mov_b32_e32 v110, 0
	v_mov_b32_e32 v111, 0
	v_mov_b32_e32 v163, 1.0
	s_and_saveexec_b64 s[6:7], s[10:11]
	v_mul_hi_i32_i24_e32 v135, v22, v86
	v_mul_i32_i24_e32 v134, v22, v86
	v_lshl_add_u64 v[134:135], v[134:135], 2, v[20:21]
	global_load_dwordx4 v[108:111], v[134:135], off nt
	s_and_saveexec_b64 s[10:11], vcc
	v_lshl_add_u64 v[150:151], s[8:9], 0, v[8:9]
	v_lshl_add_u64 v[150:151], v[150:151], 2, v[18:19]
	global_load_dword v163, v[150:151], off offset:96
	s_or_b64 exec, exec, s[10:11]
	s_or_b64 exec, exec, s[6:7]
	v_or_b32_e32 v88, s8, v28
	v_cmp_lt_i32_e64 s[6:7], v88, v33
	s_and_b64 s[10:11], s[4:5], s[6:7]
	v_mov_b32_e32 v112, 0
	v_mov_b32_e32 v113, 0
	v_mov_b32_e32 v114, 0
	v_mov_b32_e32 v115, 0
	v_mov_b32_e32 v164, 1.0
	s_and_saveexec_b64 s[6:7], s[10:11]
	v_mul_hi_i32_i24_e32 v137, v22, v88
	v_mul_i32_i24_e32 v136, v22, v88
	v_lshl_add_u64 v[136:137], v[136:137], 2, v[20:21]
	global_load_dwordx4 v[112:115], v[136:137], off nt
	s_and_saveexec_b64 s[10:11], vcc
	v_lshl_add_u64 v[152:153], s[8:9], 0, v[8:9]
	v_lshl_add_u64 v[152:153], v[152:153], 2, v[18:19]
	global_load_dword v164, v[152:153], off offset:128
	s_or_b64 exec, exec, s[10:11]
	s_or_b64 exec, exec, s[6:7]
	v_or_b32_e32 v90, s8, v29
	v_cmp_lt_i32_e64 s[6:7], v90, v33
	s_and_b64 s[10:11], s[4:5], s[6:7]
	v_mov_b32_e32 v116, 0
	v_mov_b32_e32 v117, 0
	v_mov_b32_e32 v118, 0
	v_mov_b32_e32 v119, 0
	v_mov_b32_e32 v165, 1.0
	s_and_saveexec_b64 s[6:7], s[10:11]
	v_mul_hi_i32_i24_e32 v139, v22, v90
	v_mul_i32_i24_e32 v138, v22, v90
	v_lshl_add_u64 v[138:139], v[138:139], 2, v[20:21]
	global_load_dwordx4 v[116:119], v[138:139], off nt
	s_and_saveexec_b64 s[10:11], vcc
	v_lshl_add_u64 v[154:155], s[8:9], 0, v[8:9]
	v_lshl_add_u64 v[154:155], v[154:155], 2, v[18:19]
	global_load_dword v165, v[154:155], off offset:160
	s_or_b64 exec, exec, s[10:11]
	s_or_b64 exec, exec, s[6:7]
	v_or_b32_e32 v92, s8, v30
	v_cmp_lt_i32_e64 s[6:7], v92, v33
	s_and_b64 s[10:11], s[4:5], s[6:7]
	v_mov_b32_e32 v120, 0
	v_mov_b32_e32 v121, 0
	v_mov_b32_e32 v122, 0
	v_mov_b32_e32 v123, 0
	v_mov_b32_e32 v166, 1.0
	s_and_saveexec_b64 s[6:7], s[10:11]
	v_mul_hi_i32_i24_e32 v141, v22, v92
	v_mul_i32_i24_e32 v140, v22, v92
	v_lshl_add_u64 v[140:141], v[140:141], 2, v[20:21]
	global_load_dwordx4 v[120:123], v[140:141], off nt
	s_and_saveexec_b64 s[10:11], vcc
	v_lshl_add_u64 v[156:157], s[8:9], 0, v[8:9]
	v_lshl_add_u64 v[156:157], v[156:157], 2, v[18:19]
	global_load_dword v166, v[156:157], off offset:192
	s_or_b64 exec, exec, s[10:11]
	s_or_b64 exec, exec, s[6:7]
	v_or_b32_e32 v94, s8, v31
	v_cmp_lt_i32_e64 s[6:7], v94, v33
	s_and_b64 s[10:11], s[4:5], s[6:7]
	v_mov_b32_e32 v124, 0
	v_mov_b32_e32 v125, 0
	v_mov_b32_e32 v126, 0
	v_mov_b32_e32 v127, 0
	v_mov_b32_e32 v167, 1.0
	s_and_saveexec_b64 s[6:7], s[10:11]
	v_mul_hi_i32_i24_e32 v143, v22, v94
	v_mul_i32_i24_e32 v142, v22, v94
	v_lshl_add_u64 v[142:143], v[142:143], 2, v[20:21]
	global_load_dwordx4 v[124:127], v[142:143], off nt
	s_and_saveexec_b64 s[10:11], vcc
	v_lshl_add_u64 v[158:159], s[8:9], 0, v[8:9]
	v_lshl_add_u64 v[158:159], v[158:159], 2, v[18:19]
	global_load_dword v167, v[158:159], off offset:224
	s_or_b64 exec, exec, s[10:11]
	s_or_b64 exec, exec, s[6:7]
	s_waitcnt vmcnt(0)
	v_mul_f32_e32 v96, v96, v160
	v_mul_f32_e32 v97, v97, v160
	v_mul_f32_e32 v98, v98, v160
	v_mul_f32_e32 v99, v99, v160
	v_mul_f32_e32 v100, v100, v161
	v_mul_f32_e32 v101, v101, v161
	v_mul_f32_e32 v102, v102, v161
	v_mul_f32_e32 v103, v103, v161
	v_mul_f32_e32 v104, v104, v162
	v_mul_f32_e32 v105, v105, v162
	v_mul_f32_e32 v106, v106, v162
	v_mul_f32_e32 v107, v107, v162
	v_mul_f32_e32 v108, v108, v163
	v_mul_f32_e32 v109, v109, v163
	v_mul_f32_e32 v110, v110, v163
	v_mul_f32_e32 v111, v111, v163
	v_mul_f32_e32 v112, v112, v164
	v_mul_f32_e32 v113, v113, v164
	v_mul_f32_e32 v114, v114, v164
	v_mul_f32_e32 v115, v115, v164
	v_mul_f32_e32 v116, v116, v165
	v_mul_f32_e32 v117, v117, v165
	v_mul_f32_e32 v118, v118, v165
	v_mul_f32_e32 v119, v119, v165
	v_mul_f32_e32 v120, v120, v166
	v_mul_f32_e32 v121, v121, v166
	v_mul_f32_e32 v122, v122, v166
	v_mul_f32_e32 v123, v123, v166
	v_mul_f32_e32 v124, v124, v167
	v_mul_f32_e32 v125, v125, v167
	v_mul_f32_e32 v126, v126, v167
	v_mul_f32_e32 v127, v127, v167
	ds_write_b128 v32, v[96:99]
	ds_write_b128 v32, v[100:103] offset:1152
	ds_write_b128 v32, v[104:107] offset:2304
	ds_write_b128 v32, v[108:111] offset:3456
	ds_write_b128 v32, v[112:115] offset:4608
	ds_write_b128 v32, v[116:119] offset:5760
	ds_write_b128 v32, v[120:123] offset:6912
	ds_write_b128 v32, v[124:127] offset:8064
	s_branch .Lcv_t4_tr

.Lcv_t5_tr:
	s_waitcnt lgkmcnt(0)
	ds_read2_b32 v[2:3], v1 offset1:36
	v_or_b32_e32 v6, s1, v8
	s_waitcnt lgkmcnt(0)
	v_cvt_pk_bf16_f32 v2, v2, v3
	ds_read2_b32 v[4:5], v1 offset0:72 offset1:108
	s_ashr_i32 s11, s10, 31
	v_ashrrev_i32_e32 v7, 31, v6
	s_waitcnt lgkmcnt(0)
	v_cvt_pk_bf16_f32 v3, v4, v5
	ds_read2_b32 v[4:5], v1 offset0:144 offset1:180
	v_lshl_add_u64 v[18:19], s[10:11], 1, v[12:13]
	v_lshlrev_b64 v[6:7], 9, v[6:7]
	s_waitcnt lgkmcnt(0)
	v_cvt_pk_bf16_f32 v4, v4, v5
	ds_read2_b32 v[16:17], v1 offset0:216 offset1:252
	v_lshl_add_u64 v[6:7], v[18:19], 0, v[6:7]
	s_waitcnt lgkmcnt(0)
	v_cvt_pk_bf16_f32 v5, v16, v17
	v_or_b32_e32 v16, s1, v25
	global_store_dwordx4 v[6:7], v[2:5], off sc1
	s_nop 1
	ds_read2_b32 v[2:3], v1 offset0:8 offset1:44
	s_waitcnt lgkmcnt(0)
	v_cvt_pk_bf16_f32 v2, v2, v3
	ds_read2_b32 v[4:5], v1 offset0:80 offset1:116
	v_ashrrev_i32_e32 v17, 31, v16
	s_waitcnt lgkmcnt(0)
	v_cvt_pk_bf16_f32 v3, v4, v5
	ds_read2_b32 v[4:5], v1 offset0:152 offset1:188
	v_add_u32_e32 v10, 0x200, v1
	v_lshlrev_b64 v[16:17], 9, v[16:17]
	s_waitcnt lgkmcnt(0)
	v_cvt_pk_bf16_f32 v4, v4, v5
	ds_read2_b32 v[6:7], v10 offset0:96 offset1:132
	v_lshl_add_u64 v[16:17], v[18:19], 0, v[16:17]
	s_waitcnt lgkmcnt(0)
	v_cvt_pk_bf16_f32 v5, v6, v7
	s_addk_i32 s0, 0x400
	global_store_dwordx4 v[16:17], v[2:5], off sc1
	s_nop 1
	ds_read2_b32 v[2:3], v1 offset0:16 offset1:52
	v_or_b32_e32 v16, s1, v26
	s_waitcnt lgkmcnt(0)
	v_cvt_pk_bf16_f32 v2, v2, v3
	ds_read2_b32 v[4:5], v1 offset0:88 offset1:124
	v_ashrrev_i32_e32 v17, 31, v16
	s_waitcnt lgkmcnt(0)
	v_cvt_pk_bf16_f32 v3, v4, v5
	ds_read2_b32 v[4:5], v1 offset0:160 offset1:196
	v_lshlrev_b64 v[16:17], 9, v[16:17]
	s_waitcnt lgkmcnt(0)
	v_cvt_pk_bf16_f32 v4, v4, v5
	ds_read2_b32 v[6:7], v10 offset0:104 offset1:140
	v_lshl_add_u64 v[16:17], v[18:19], 0, v[16:17]
	s_waitcnt lgkmcnt(0)
	v_cvt_pk_bf16_f32 v5, v6, v7
	s_cmpk_lt_u32 s0, 0x160
	global_store_dwordx4 v[16:17], v[2:5], off sc1
	s_nop 1
	ds_read2_b32 v[2:3], v1 offset0:24 offset1:60
	v_or_b32_e32 v16, s1, v27
	s_waitcnt lgkmcnt(0)
	v_cvt_pk_bf16_f32 v2, v2, v3
	ds_read2_b32 v[4:5], v1 offset0:96 offset1:132
	v_ashrrev_i32_e32 v17, 31, v16
	s_waitcnt lgkmcnt(0)
	v_cvt_pk_bf16_f32 v3, v4, v5
	ds_read2_b32 v[4:5], v1 offset0:168 offset1:204
	v_lshlrev_b64 v[16:17], 9, v[16:17]
	s_waitcnt lgkmcnt(0)
	v_cvt_pk_bf16_f32 v4, v4, v5
	ds_read2_b32 v[6:7], v10 offset0:112 offset1:148
	v_lshl_add_u64 v[16:17], v[18:19], 0, v[16:17]
	s_waitcnt lgkmcnt(0)
	v_cvt_pk_bf16_f32 v5, v6, v7
	s_nop 0
	global_store_dwordx4 v[16:17], v[2:5], off sc1
	s_nop 1
	s_waitcnt lgkmcnt(0)
	s_cbranch_scc0 .LBB0_502

.LBB0_478:
	s_sext_i32_i16 s4, s12
	s_lshl_b32 s10, s4, 6
	s_cmp_lg_u64 s[8:9], 0
	s_cselect_b64 s[4:5], -1, 0
	v_cmp_ne_u64_e64 s[6:7], 0, v[16:17]
	s_ashr_i32 s11, s10, 31
	v_or_b32_e32 v80, s10, v8
	v_cmp_gt_i32_e32 vcc, s2, v80
	s_and_b64 s[12:13], s[6:7], vcc
	v_mov_b32_e32 v96, 0
	v_mov_b32_e32 v97, 0
	v_mov_b32_e32 v98, 0
	v_mov_b32_e32 v99, 0
	v_mov_b32_e32 v160, 1.0
	s_and_saveexec_b64 s[26:27], s[12:13]
	v_mul_hi_i32_i24_e32 v129, s24, v80
	v_mul_i32_i24_e32 v128, s24, v80
	v_lshl_add_u64 v[128:129], v[128:129], 2, v[16:17]
	global_load_dwordx4 v[96:99], v[128:129], off nt
	s_and_saveexec_b64 s[12:13], s[4:5]
	v_lshl_add_u64 v[144:145], s[10:11], 0, v[8:9]
	v_lshl_add_u64 v[144:145], v[144:145], 2, s[8:9]
	global_load_dword v160, v[144:145], off
	s_or_b64 exec, exec, s[12:13]
	s_or_b64 exec, exec, s[26:27]
	v_or_b32_e32 v82, s10, v25
	v_cmp_gt_i32_e32 vcc, s2, v82
	s_and_b64 s[12:13], s[6:7], vcc
	v_mov_b32_e32 v100, 0
	v_mov_b32_e32 v101, 0
	v_mov_b32_e32 v102, 0
	v_mov_b32_e32 v103, 0
	v_mov_b32_e32 v161, 1.0
	s_and_saveexec_b64 s[26:27], s[12:13]
	v_mul_hi_i32_i24_e32 v131, s24, v82
	v_mul_i32_i24_e32 v130, s24, v82
	v_lshl_add_u64 v[130:131], v[130:131], 2, v[16:17]
	global_load_dwordx4 v[100:103], v[130:131], off nt
	s_and_saveexec_b64 s[12:13], s[4:5]
	v_lshl_add_u64 v[146:147], s[10:11], 0, v[8:9]
	v_lshl_add_u64 v[146:147], v[146:147], 2, s[8:9]
	global_load_dword v161, v[146:147], off offset:32
	s_or_b64 exec, exec, s[12:13]
	s_or_b64 exec, exec, s[26:27]
	v_or_b32_e32 v84, s10, v26
	v_cmp_gt_i32_e32 vcc, s2, v84
	s_and_b64 s[12:13], s[6:7], vcc
	v_mov_b32_e32 v104, 0
	v_mov_b32_e32 v105, 0
	v_mov_b32_e32 v106, 0
	v_mov_b32_e32 v107, 0
	v_mov_b32_e32 v162, 1.0
	s_and_saveexec_b64 s[26:27], s[12:13]
	v_mul_hi_i32_i24_e32 v133, s24, v84
	v_mul_i32_i24_e32 v132, s24, v84
	v_lshl_add_u64 v[132:133], v[132:133], 2, v[16:17]
	global_load_dwordx4 v[104:107], v[132:133], off nt
	s_and_saveexec_b64 s[12:13], s[4:5]
	v_lshl_add_u64 v[148:149], s[10:11], 0, v[8:9]
	v_lshl_add_u64 v[148:149], v[148:149], 2, s[8:9]
	global_load_dword v162, v[148:149], off offset:64
	s_or_b64 exec, exec, s[12:13]
	s_or_b64 exec, exec, s[26:27]
	v_or_b32_e32 v86, s10, v27
	v_cmp_gt_i32_e32 vcc, s2, v86
	s_and_b64 s[12:13], s[6:7], vcc
	v_mov_b32_e32 v108, 0
	v_mov_b32_e32 v109, 0
	v_mov_b32_e32 v110, 0
	v_mov_b32_e32 v111, 0
	v_mov_b32_e32 v163, 1.0
	s_and_saveexec_b64 s[26:27], s[12:13]
	v_mul_hi_i32_i24_e32 v135, s24, v86
	v_mul_i32_i24_e32 v134, s24, v86
	v_lshl_add_u64 v[134:135], v[134:135], 2, v[16:17]
	global_load_dwordx4 v[108:111], v[134:135], off nt
	s_and_saveexec_b64 s[12:13], s[4:5]
	v_lshl_add_u64 v[150:151], s[10:11], 0, v[8:9]
	v_lshl_add_u64 v[150:151], v[150:151], 2, s[8:9]
	global_load_dword v163, v[150:151], off offset:96
	s_or_b64 exec, exec, s[12:13]
	s_or_b64 exec, exec, s[26:27]
	v_or_b32_e32 v88, s10, v28
	v_cmp_gt_i32_e32 vcc, s2, v88
	s_and_b64 s[12:13], s[6:7], vcc
	v_mov_b32_e32 v112, 0
	v_mov_b32_e32 v113, 0
	v_mov_b32_e32 v114, 0
	v_mov_b32_e32 v115, 0
	v_mov_b32_e32 v164, 1.0
	s_and_saveexec_b64 s[26:27], s[12:13]
	v_mul_hi_i32_i24_e32 v137, s24, v88
	v_mul_i32_i24_e32 v136, s24, v88
	v_lshl_add_u64 v[136:137], v[136:137], 2, v[16:17]
	global_load_dwordx4 v[112:115], v[136:137], off nt
	s_and_saveexec_b64 s[12:13], s[4:5]
	v_lshl_add_u64 v[152:153], s[10:11], 0, v[8:9]
	v_lshl_add_u64 v[152:153], v[152:153], 2, s[8:9]
	global_load_dword v164, v[152:153], off offset:128
	s_or_b64 exec, exec, s[12:13]
	s_or_b64 exec, exec, s[26:27]
	v_or_b32_e32 v90, s10, v29
	v_cmp_gt_i32_e32 vcc, s2, v90
	s_and_b64 s[12:13], s[6:7], vcc
	v_mov_b32_e32 v116, 0
	v_mov_b32_e32 v117, 0
	v_mov_b32_e32 v118, 0
	v_mov_b32_e32 v119, 0
	v_mov_b32_e32 v165, 1.0
	s_and_saveexec_b64 s[26:27], s[12:13]
	v_mul_hi_i32_i24_e32 v139, s24, v90
	v_mul_i32_i24_e32 v138, s24, v90
	v_lshl_add_u64 v[138:139], v[138:139], 2, v[16:17]
	global_load_dwordx4 v[116:119], v[138:139], off nt
	s_and_saveexec_b64 s[12:13], s[4:5]
	v_lshl_add_u64 v[154:155], s[10:11], 0, v[8:9]
	v_lshl_add_u64 v[154:155], v[154:155], 2, s[8:9]
	global_load_dword v165, v[154:155], off offset:160
	s_or_b64 exec, exec, s[12:13]
	s_or_b64 exec, exec, s[26:27]
	v_or_b32_e32 v92, s10, v30
	v_cmp_gt_i32_e32 vcc, s2, v92
	s_and_b64 s[12:13], s[6:7], vcc
	v_mov_b32_e32 v120, 0
	v_mov_b32_e32 v121, 0
	v_mov_b32_e32 v122, 0
	v_mov_b32_e32 v123, 0
	v_mov_b32_e32 v166, 1.0
	s_and_saveexec_b64 s[26:27], s[12:13]
	v_mul_hi_i32_i24_e32 v141, s24, v92
	v_mul_i32_i24_e32 v140, s24, v92
	v_lshl_add_u64 v[140:141], v[140:141], 2, v[16:17]
	global_load_dwordx4 v[120:123], v[140:141], off nt
	s_and_saveexec_b64 s[12:13], s[4:5]
	v_lshl_add_u64 v[156:157], s[10:11], 0, v[8:9]
	v_lshl_add_u64 v[156:157], v[156:157], 2, s[8:9]
	global_load_dword v166, v[156:157], off offset:192
	s_or_b64 exec, exec, s[12:13]
	s_or_b64 exec, exec, s[26:27]
	v_or_b32_e32 v94, s10, v31
	v_cmp_gt_i32_e32 vcc, s2, v94
	s_and_b64 s[12:13], s[6:7], vcc
	v_mov_b32_e32 v124, 0
	v_mov_b32_e32 v125, 0
	v_mov_b32_e32 v126, 0
	v_mov_b32_e32 v127, 0
	v_mov_b32_e32 v167, 1.0
	s_and_saveexec_b64 s[26:27], s[12:13]
	v_mul_hi_i32_i24_e32 v143, s24, v94
	v_mul_i32_i24_e32 v142, s24, v94
	v_lshl_add_u64 v[142:143], v[142:143], 2, v[16:17]
	global_load_dwordx4 v[124:127], v[142:143], off nt
	s_and_saveexec_b64 s[12:13], s[4:5]
	v_lshl_add_u64 v[158:159], s[10:11], 0, v[8:9]
	v_lshl_add_u64 v[158:159], v[158:159], 2, s[8:9]
	global_load_dword v167, v[158:159], off offset:224
	s_or_b64 exec, exec, s[12:13]
	s_or_b64 exec, exec, s[26:27]
	s_waitcnt vmcnt(0)
	v_mul_f32_e32 v96, v96, v160
	v_mul_f32_e32 v97, v97, v160
	v_mul_f32_e32 v98, v98, v160
	v_mul_f32_e32 v99, v99, v160
	v_mul_f32_e32 v100, v100, v161
	v_mul_f32_e32 v101, v101, v161
	v_mul_f32_e32 v102, v102, v161
	v_mul_f32_e32 v103, v103, v161
	v_mul_f32_e32 v104, v104, v162
	v_mul_f32_e32 v105, v105, v162
	v_mul_f32_e32 v106, v106, v162
	v_mul_f32_e32 v107, v107, v162
	v_mul_f32_e32 v108, v108, v163
	v_mul_f32_e32 v109, v109, v163
	v_mul_f32_e32 v110, v110, v163
	v_mul_f32_e32 v111, v111, v163
	v_mul_f32_e32 v112, v112, v164
	v_mul_f32_e32 v113, v113, v164
	v_mul_f32_e32 v114, v114, v164
	v_mul_f32_e32 v115, v115, v164
	v_mul_f32_e32 v116, v116, v165
	v_mul_f32_e32 v117, v117, v165
	v_mul_f32_e32 v118, v118, v165
	v_mul_f32_e32 v119, v119, v165
	v_mul_f32_e32 v120, v120, v166
	v_mul_f32_e32 v121, v121, v166
	v_mul_f32_e32 v122, v122, v166
	v_mul_f32_e32 v123, v123, v166
	v_mul_f32_e32 v124, v124, v167
	v_mul_f32_e32 v125, v125, v167
	v_mul_f32_e32 v126, v126, v167
	v_mul_f32_e32 v127, v127, v167
	ds_write_b128 v32, v[96:99]
	ds_write_b128 v32, v[100:103] offset:1152
	ds_write_b128 v32, v[104:107] offset:2304
	ds_write_b128 v32, v[108:111] offset:3456
	ds_write_b128 v32, v[112:115] offset:4608
	ds_write_b128 v32, v[116:119] offset:5760
	ds_write_b128 v32, v[120:123] offset:6912
	ds_write_b128 v32, v[124:127] offset:8064
	s_branch .Lcv_t5_tr
